# attention loop LDS-DMA block in saddr form: per-lane byte offsets kept per pass in v213/v215/v217, the six per-tile 64-bit VALU address adds replaced by SALU adds on the SGPR base
# speedup vs baseline: 1.0077x; 1.0077x over previous
.LBB0_509:
	s_xor_b64 s[18:19], s[4:5], -1
	s_lshl_b64 s[4:5], s[0:1], 1
	s_add_u32 s22, s56, s4
	s_addc_u32 s23, s57, s5
	v_mov_b32_e32 v2, v208
	s_add_u32 s0, s58, s4
	s_addc_u32 s1, s59, s5
	v_readfirstlane_b32 s20, v2
	s_ashr_i32 s24, s20, 6
	s_and_b32 s20, s20, 0x3fffffc0
	s_lshl_b32 s20, s20, 2
	v_and_b32_e32 v219, 31, v2
	s_add_i32 s21, s20, 0
	s_lshl_b32 s20, s24, 5
	v_or_b32_e32 v0, s20, v219
	s_waitcnt lgkmcnt(0)
	v_ashrrev_i32_e32 v1, 31, v0
	v_bfe_u32 v218, v2, 5, 1
	v_lshlrev_b64 v[0:1], 11, v[0:1]
	v_lshl_add_u64 v[0:1], s[22:23], 0, v[0:1]
	v_lshlrev_b32_e32 v210, 4, v218
	v_lshl_add_u64 v[0:1], v[0:1], 0, v[210:211]
	global_load_dwordx4 v[160:163], v[0:1], off
	global_load_dwordx4 v[164:167], v[0:1], off offset:32
	global_load_dwordx4 v[168:171], v[0:1], off offset:64
	global_load_dwordx4 v[172:175], v[0:1], off offset:96
	global_load_dwordx4 v[176:179], v[0:1], off offset:128
	global_load_dwordx4 v[180:183], v[0:1], off offset:160
	global_load_dwordx4 v[184:187], v[0:1], off offset:192
	global_load_dwordx4 v[188:191], v[0:1], off offset:224
	s_lshl_b32 s22, s24, 3
	v_bfe_u32 v1, v2, 4, 2
	v_or_b32_e32 v0, s22, v1
	v_bitop3_b32 v4, v1, v2, 15 bitop3:0x78
	v_ashrrev_i32_e32 v1, 31, v0
	v_lshlrev_b64 v[212:213], 10, v[0:1]
	v_or_b32_e32 v0, 4, v0
	v_and_b32_e32 v3, 15, v2
	v_ashrrev_i32_e32 v1, 31, v0
	v_bitop3_b32 v3, v0, v3, 7 bitop3:0x6c
	s_and_b32 s25, s24, 1
	s_lshl_b32 s25, s25, 3
	v_xor_b32_e32 v4, s25, v4
	v_xor_b32_e32 v3, s25, v3
	v_lshlrev_b64 v[214:215], 10, v[0:1]
	v_bfe_u32 v0, v2, 2, 3
	v_bitop3_b32 v0, s22, -13, v0 bitop3:0xc8
	v_lshrrev_b32_e32 v1, 2, v2
	s_lshl_b32 s22, s24, 3
	v_and_b32_e32 v1, 4, v1
	s_and_b32 s22, s22, 8
	v_or3_b32 v0, v0, v1, s22
	s_add_i32 s21, s21, 0x24000
	v_ashrrev_i32_e32 v1, 31, v0
	v_lshlrev_b32_e32 v11, 3, v2
	s_lshl_b32 s22, s24, 11
	v_lshl_or_b32 v212, v4, 3, v212
	v_lshlrev_b64 v[216:217], 10, v[0:1]
	v_and_b32_e32 v0, 32, v2
	v_and_b32_e32 v1, 24, v11
	s_cmp_lg_u32 0, -1
	v_or3_b32 v216, v216, v1, v0
	v_lshlrev_b64 v[0:1], 1, v[212:213]
	s_cselect_b32 s23, 0, 0
	v_and_b32_e32 v10, 63, v2
	v_lshl_or_b32 v214, v3, 3, v214
	v_lshlrev_b32_e32 v12, 4, v2
	v_lshlrev_b32_e32 v13, 1, v2
	v_lshl_add_u64 v[2:3], s[0:1], 0, v[0:1]
	s_add_i32 s75, s22, s23
	s_mov_b32 s25, m0
	s_mov_b32 m0, s75
	s_nop 0
	global_load_lds_dwordx4 v[2:3], off
	s_mov_b32 m0, s25
	v_lshlrev_b64 v[2:3], 1, v[214:215]
	s_or_b32 s25, s22, 0x400
	v_lshl_add_u64 v[4:5], s[0:1], 0, v[2:3]
	s_add_i32 s77, s25, s23
	s_mov_b32 s84, m0
	s_mov_b32 m0, s77
	s_nop 0
	global_load_lds_dwordx4 v[4:5], off
	s_mov_b32 m0, s84
	s_lshl_b32 s24, s24, 12
	v_lshlrev_b64 v[4:5], 1, v[216:217]
	v_lshlrev_b32_e32 v213, 1, v212
	v_lshlrev_b32_e32 v215, 1, v214
	v_lshlrev_b32_e32 v217, 1, v216
	s_add_i32 s84, s23, 0xc000
	v_lshl_add_u64 v[6:7], s[14:15], 0, v[4:5]
	s_add_i32 s77, s24, s84
	s_mov_b32 s85, m0
	s_mov_b32 m0, s77
	s_nop 0
	global_load_lds_dwordx4 v[6:7], off
	s_mov_b32 m0, s85
	s_or_b32 s85, s24, 0x400
	s_add_i32 s86, s85, s84
	v_lshl_add_u64 v[8:9], v[6:7], 0, s[8:9]
	s_mov_b32 s87, m0
	s_mov_b32 m0, s86
	s_nop 0
	global_load_lds_dwordx4 v[8:9], off
	s_mov_b32 m0, s87
	s_or_b32 s86, s24, 0x800
	s_add_i32 s87, s86, s84
	v_lshl_add_u64 v[8:9], v[6:7], 0, s[10:11]
	s_mov_b32 s96, m0
	s_mov_b32 m0, s87
	s_nop 0
	global_load_lds_dwordx4 v[8:9], off
	s_mov_b32 m0, s96
	s_or_b32 s87, s24, 0xc00
	s_add_i32 s96, s87, s84
	s_add_u32 s0, s0, 0x20000
	v_lshl_add_u64 v[6:7], v[6:7], 0, s[12:13]
	s_mov_b32 s97, m0
	s_mov_b32 m0, s96
	s_nop 0
	global_load_lds_dwordx4 v[6:7], off
	s_mov_b32 m0, s97
	s_addc_u32 s1, s1, 0
	s_add_i32 s96, s23, 0x4000
	v_lshl_add_u64 v[0:1], s[0:1], 0, v[0:1]
	s_add_i32 s22, s22, s96
	s_mov_b32 s97, m0
	s_mov_b32 m0, s22
	s_nop 0
	global_load_lds_dwordx4 v[0:1], off
	s_mov_b32 m0, s97
	v_lshl_add_u64 v[0:1], s[0:1], 0, v[2:3]
	s_add_i32 s25, s25, s96
	s_mov_b32 s0, m0
	s_mov_b32 m0, s25
	s_nop 0
	global_load_lds_dwordx4 v[0:1], off
	s_mov_b32 m0, s0
	s_add_i32 s23, s23, 0x14000
	v_lshl_add_u64 v[0:1], s[16:17], 0, v[4:5]
	s_add_i32 s24, s24, s23
	s_mov_b32 s0, m0
	s_mov_b32 m0, s24
	s_nop 0
	global_load_lds_dwordx4 v[0:1], off
	s_mov_b32 m0, s0
	v_lshl_add_u64 v[2:3], v[0:1], 0, s[8:9]
	s_add_i32 s85, s85, s23
	s_mov_b32 s0, m0
	s_mov_b32 m0, s85
	s_nop 0
	global_load_lds_dwordx4 v[2:3], off
	s_mov_b32 m0, s0
	v_lshl_add_u64 v[2:3], v[0:1], 0, s[10:11]
	s_add_i32 s86, s86, s23
	s_mov_b32 s0, m0
	s_mov_b32 m0, s86
	s_nop 0
	global_load_lds_dwordx4 v[2:3], off
	s_mov_b32 m0, s0
	v_lshl_add_u64 v[0:1], v[0:1], 0, s[12:13]
	s_add_i32 s87, s87, s23
	s_mov_b32 s0, m0
	s_mov_b32 m0, s87
	s_nop 0
	global_load_lds_dwordx4 v[0:1], off
	s_mov_b32 m0, s0
	s_movk_i32 s0, 0x70
	v_and_b32_e32 v1, 0x70, v12
	v_bitop3_b32 v221, v210, v12, s0 bitop3:0x78
	s_movk_i32 s0, 0x60
	v_bitop3_b32 v224, v210, v1, s0 bitop3:0x36
	s_movk_i32 s0, 0x80
	v_and_b32_e32 v0, 0x118, v11
	v_bitop3_b32 v225, v210, v1, s0 bitop3:0x36
	s_movk_i32 s0, 0xa0
	v_and_b32_e32 v14, 0xc0, v12
	v_bitop3_b32 v227, v210, v1, s0 bitop3:0x36
	s_movk_i32 s0, 0xc0
	v_and_or_b32 v0, v13, 32, v0
	v_bitop3_b32 v228, v210, v1, s0 bitop3:0x36
	s_movk_i32 s0, 0xe0
	v_add3_u32 v230, v14, s84, v0
	v_mov_b32_e32 v14, v211
	v_mov_b32_e32 v15, v211
	v_bitop3_b32 v222, v210, v1, 32 bitop3:0x36
	v_bitop3_b32 v223, v210, v1, 64 bitop3:0x36
	v_bitop3_b32 v229, v210, v1, s0 bitop3:0x36
	v_and_b32_e32 v236, 0x80, v12
	v_xor_b32_e32 v221, v236, v221
	v_xor_b32_e32 v222, v236, v222
	v_xor_b32_e32 v223, v236, v223
	v_xor_b32_e32 v224, v236, v224
	v_xor_b32_e32 v225, v236, v225
	v_xor_b32_e32 v227, v236, v227
	v_xor_b32_e32 v228, v236, v228
	v_xor_b32_e32 v229, v236, v229
	v_cmp_gt_u32_e64 s[0:1], 32, v10
	s_add_u32 s84, s66, s4
	v_mov_b32_e32 v0, v211
	v_mov_b32_e32 v1, v211
	v_mov_b32_e32 v2, v211
	v_mov_b32_e32 v3, v211
	v_mov_b32_e32 v4, v211
	v_mov_b32_e32 v5, v211
	v_mov_b32_e32 v6, v211
	v_mov_b32_e32 v7, v211
	v_mov_b32_e32 v8, v211
	v_mov_b32_e32 v9, v211
	v_mov_b32_e32 v10, v211
	v_mov_b32_e32 v11, v211
	v_mov_b32_e32 v12, v211
	v_mov_b32_e32 v13, v211
	v_mov_b64_e32 v[126:127], v[14:15]
	v_mov_b64_e32 v[110:111], v[14:15]
	v_mov_b64_e32 v[94:95], v[14:15]
	v_mov_b64_e32 v[78:79], v[14:15]
	v_mov_b64_e32 v[62:63], v[14:15]
	v_mov_b64_e32 v[46:47], v[14:15]
	v_mov_b64_e32 v[30:31], v[14:15]
	s_mov_b32 s74, 2
	s_mov_b32 s76, 0
	v_lshlrev_b32_e32 v220, 8, v219
	v_lshl_add_u32 v226, v219, 2, s21
	s_addc_u32 s85, s67, s5
	v_mov_b32_e32 v232, 0
	v_mov_b32_e32 v231, 0xf149f2ca
	s_mov_b64 s[22:23], 0
	v_mov_b64_e32 v[124:125], v[12:13]
	v_mov_b64_e32 v[122:123], v[10:11]
	v_mov_b64_e32 v[120:121], v[8:9]
	v_mov_b64_e32 v[118:119], v[6:7]
	v_mov_b64_e32 v[116:117], v[4:5]
	v_mov_b64_e32 v[114:115], v[2:3]
	v_mov_b64_e32 v[112:113], v[0:1]
	v_mov_b64_e32 v[108:109], v[12:13]
	v_mov_b64_e32 v[106:107], v[10:11]
	v_mov_b64_e32 v[104:105], v[8:9]
	v_mov_b64_e32 v[102:103], v[6:7]
	v_mov_b64_e32 v[100:101], v[4:5]
	v_mov_b64_e32 v[98:99], v[2:3]
	v_mov_b64_e32 v[96:97], v[0:1]
	v_mov_b64_e32 v[92:93], v[12:13]
	v_mov_b64_e32 v[90:91], v[10:11]
	v_mov_b64_e32 v[88:89], v[8:9]
	v_mov_b64_e32 v[86:87], v[6:7]
	v_mov_b64_e32 v[84:85], v[4:5]
	v_mov_b64_e32 v[82:83], v[2:3]
	v_mov_b64_e32 v[80:81], v[0:1]
	v_mov_b64_e32 v[76:77], v[12:13]
	v_mov_b64_e32 v[74:75], v[10:11]
	v_mov_b64_e32 v[72:73], v[8:9]
	v_mov_b64_e32 v[70:71], v[6:7]
	v_mov_b64_e32 v[68:69], v[4:5]
	v_mov_b64_e32 v[66:67], v[2:3]
	v_mov_b64_e32 v[64:65], v[0:1]
	v_mov_b64_e32 v[60:61], v[12:13]
	v_mov_b64_e32 v[58:59], v[10:11]
	v_mov_b64_e32 v[56:57], v[8:9]
	v_mov_b64_e32 v[54:55], v[6:7]
	v_mov_b64_e32 v[52:53], v[4:5]
	v_mov_b64_e32 v[50:51], v[2:3]
	v_mov_b64_e32 v[48:49], v[0:1]
	v_mov_b64_e32 v[44:45], v[12:13]
	v_mov_b64_e32 v[42:43], v[10:11]
	v_mov_b64_e32 v[40:41], v[8:9]
	v_mov_b64_e32 v[38:39], v[6:7]
	v_mov_b64_e32 v[36:37], v[4:5]
	v_mov_b64_e32 v[34:35], v[2:3]
	v_mov_b64_e32 v[32:33], v[0:1]
	v_mov_b64_e32 v[28:29], v[12:13]
	v_mov_b64_e32 v[26:27], v[10:11]
	v_mov_b64_e32 v[24:25], v[8:9]
	v_mov_b64_e32 v[22:23], v[6:7]
	v_mov_b64_e32 v[20:21], v[4:5]
	v_mov_b64_e32 v[18:19], v[2:3]
	v_mov_b64_e32 v[16:17], v[0:1]
	s_mov_b32 s86, 0
	s_cmp_eq_u32 s22, 0x7e0000
	s_mov_b64 s[4:5], -1
	s_cbranch_scc0 .LBB0_519

.LBB0_512:
	s_lshl_b32 s24, s74, 14
	s_add_i32 s24, s75, s24
	s_mov_b32 m0, s24
	s_add_u32 s96, s84, s22
	s_addc_u32 s97, s85, s23
	global_load_lds_dwordx4 v213, s[96:97]
	s_add_i32 m0, s24, 0x400
	s_add_u32 s4, s68, s22
	s_addc_u32 s5, s69, s23
	s_add_u32 s4, s4, 0x26840000
	s_addc_u32 s5, s5, 0
	global_load_lds_dwordx4 v215, s[96:97]
	s_lshl_b32 s24, s74, 15
	s_add_i32 s24, s77, s24
	s_mov_b32 m0, s24
	s_add_u32 s96, s4, s8
	s_addc_u32 s97, s5, s9
	global_load_lds_dwordx4 v217, s[4:5]
	s_add_i32 m0, s24, 0x400
	s_nop 0
	global_load_lds_dwordx4 v217, s[96:97]
	s_add_i32 m0, s24, 0x800
	s_add_u32 s96, s4, s10
	s_addc_u32 s97, s5, s11
	global_load_lds_dwordx4 v217, s[96:97]
	s_add_i32 m0, s24, 0xc00
	s_add_u32 s96, s4, s12
	s_addc_u32 s97, s5, s13
	global_load_lds_dwordx4 v217, s[96:97]

.LBB0_902:
	s_xor_b64 s[18:19], s[4:5], -1
	s_lshl_b64 s[4:5], s[0:1], 1
	s_add_u32 s22, s62, s4
	s_addc_u32 s23, s63, s5
	v_mov_b32_e32 v2, v208
	s_add_u32 s0, s64, s4
	s_addc_u32 s1, s65, s5
	v_readfirstlane_b32 s20, v2
	s_ashr_i32 s24, s20, 6
	s_and_b32 s20, s20, 0x3fffffc0
	s_lshl_b32 s20, s20, 2
	v_and_b32_e32 v219, 31, v2
	s_add_i32 s21, s20, 0
	s_lshl_b32 s20, s24, 5
	v_or_b32_e32 v0, s20, v219
	s_waitcnt lgkmcnt(0)
	v_ashrrev_i32_e32 v1, 31, v0
	v_bfe_u32 v218, v2, 5, 1
	v_lshlrev_b64 v[0:1], 11, v[0:1]
	v_lshl_add_u64 v[0:1], s[22:23], 0, v[0:1]
	v_lshlrev_b32_e32 v210, 4, v218
	v_lshl_add_u64 v[0:1], v[0:1], 0, v[210:211]
	global_load_dwordx4 v[160:163], v[0:1], off
	global_load_dwordx4 v[164:167], v[0:1], off offset:32
	global_load_dwordx4 v[168:171], v[0:1], off offset:64
	global_load_dwordx4 v[172:175], v[0:1], off offset:96
	global_load_dwordx4 v[176:179], v[0:1], off offset:128
	global_load_dwordx4 v[180:183], v[0:1], off offset:160
	global_load_dwordx4 v[184:187], v[0:1], off offset:192
	global_load_dwordx4 v[188:191], v[0:1], off offset:224
	s_lshl_b32 s22, s24, 3
	v_bfe_u32 v1, v2, 4, 2
	v_or_b32_e32 v0, s22, v1
	v_bitop3_b32 v4, v1, v2, 15 bitop3:0x78
	v_ashrrev_i32_e32 v1, 31, v0
	v_lshlrev_b64 v[212:213], 10, v[0:1]
	v_or_b32_e32 v0, 4, v0
	v_and_b32_e32 v3, 15, v2
	v_ashrrev_i32_e32 v1, 31, v0
	v_bitop3_b32 v3, v0, v3, 7 bitop3:0x6c
	s_and_b32 s25, s24, 1
	s_lshl_b32 s25, s25, 3
	v_xor_b32_e32 v4, s25, v4
	v_xor_b32_e32 v3, s25, v3
	v_lshlrev_b64 v[214:215], 10, v[0:1]
	v_bfe_u32 v0, v2, 2, 3
	v_bitop3_b32 v0, s22, -13, v0 bitop3:0xc8
	v_lshrrev_b32_e32 v1, 2, v2
	s_lshl_b32 s22, s24, 3
	v_and_b32_e32 v1, 4, v1
	s_and_b32 s22, s22, 8
	v_or3_b32 v0, v0, v1, s22
	s_add_i32 s21, s21, 0x24000
	v_ashrrev_i32_e32 v1, 31, v0
	v_lshlrev_b32_e32 v11, 3, v2
	s_lshl_b32 s22, s24, 11
	v_lshl_or_b32 v212, v4, 3, v212
	v_lshlrev_b64 v[216:217], 10, v[0:1]
	v_and_b32_e32 v0, 32, v2
	v_and_b32_e32 v1, 24, v11
	s_cmp_lg_u32 0, -1
	v_or3_b32 v216, v216, v1, v0
	v_lshlrev_b64 v[0:1], 1, v[212:213]
	s_cselect_b32 s23, 0, 0
	v_and_b32_e32 v10, 63, v2
	v_lshl_or_b32 v214, v3, 3, v214
	v_lshlrev_b32_e32 v12, 4, v2
	v_lshlrev_b32_e32 v13, 1, v2
	v_lshl_add_u64 v[2:3], s[0:1], 0, v[0:1]
	s_add_i32 s79, s22, s23
	s_mov_b32 s25, m0
	s_mov_b32 m0, s79
	s_nop 0
	global_load_lds_dwordx4 v[2:3], off
	s_mov_b32 m0, s25
	v_lshlrev_b64 v[2:3], 1, v[214:215]
	s_or_b32 s25, s22, 0x400
	v_lshl_add_u64 v[4:5], s[0:1], 0, v[2:3]
	s_add_i32 s81, s25, s23
	s_mov_b32 s84, m0
	s_mov_b32 m0, s81
	s_nop 0
	global_load_lds_dwordx4 v[4:5], off
	s_mov_b32 m0, s84
	s_lshl_b32 s24, s24, 12
	v_lshlrev_b64 v[4:5], 1, v[216:217]
	v_lshlrev_b32_e32 v213, 1, v212
	v_lshlrev_b32_e32 v215, 1, v214
	v_lshlrev_b32_e32 v217, 1, v216
	s_add_i32 s84, s23, 0xc000
	v_lshl_add_u64 v[6:7], s[14:15], 0, v[4:5]
	s_add_i32 s81, s24, s84
	s_mov_b32 s85, m0
	s_mov_b32 m0, s81
	s_nop 0
	global_load_lds_dwordx4 v[6:7], off
	s_mov_b32 m0, s85
	s_or_b32 s85, s24, 0x400
	s_add_i32 s86, s85, s84
	v_lshl_add_u64 v[8:9], v[6:7], 0, s[8:9]
	s_mov_b32 s87, m0
	s_mov_b32 m0, s86
	s_nop 0
	global_load_lds_dwordx4 v[8:9], off
	s_mov_b32 m0, s87
	s_or_b32 s86, s24, 0x800
	s_add_i32 s87, s86, s84
	v_lshl_add_u64 v[8:9], v[6:7], 0, s[10:11]
	s_mov_b32 s96, m0
	s_mov_b32 m0, s87
	s_nop 0
	global_load_lds_dwordx4 v[8:9], off
	s_mov_b32 m0, s96
	s_or_b32 s87, s24, 0xc00
	s_add_i32 s96, s87, s84
	s_add_u32 s0, s0, 0x20000
	v_lshl_add_u64 v[6:7], v[6:7], 0, s[12:13]
	s_mov_b32 s97, m0
	s_mov_b32 m0, s96
	s_nop 0
	global_load_lds_dwordx4 v[6:7], off
	s_mov_b32 m0, s97
	s_addc_u32 s1, s1, 0
	s_add_i32 s96, s23, 0x4000
	v_lshl_add_u64 v[0:1], s[0:1], 0, v[0:1]
	s_add_i32 s22, s22, s96
	s_mov_b32 s97, m0
	s_mov_b32 m0, s22
	s_nop 0
	global_load_lds_dwordx4 v[0:1], off
	s_mov_b32 m0, s97
	v_lshl_add_u64 v[0:1], s[0:1], 0, v[2:3]
	s_add_i32 s25, s25, s96
	s_mov_b32 s0, m0
	s_mov_b32 m0, s25
	s_nop 0
	global_load_lds_dwordx4 v[0:1], off
	s_mov_b32 m0, s0
	s_add_i32 s23, s23, 0x14000
	v_lshl_add_u64 v[0:1], s[16:17], 0, v[4:5]
	s_add_i32 s24, s24, s23
	s_mov_b32 s0, m0
	s_mov_b32 m0, s24
	s_nop 0
	global_load_lds_dwordx4 v[0:1], off
	s_mov_b32 m0, s0
	v_lshl_add_u64 v[2:3], v[0:1], 0, s[8:9]
	s_add_i32 s85, s85, s23
	s_mov_b32 s0, m0
	s_mov_b32 m0, s85
	s_nop 0
	global_load_lds_dwordx4 v[2:3], off
	s_mov_b32 m0, s0
	v_lshl_add_u64 v[2:3], v[0:1], 0, s[10:11]
	s_add_i32 s86, s86, s23
	s_mov_b32 s0, m0
	s_mov_b32 m0, s86
	s_nop 0
	global_load_lds_dwordx4 v[2:3], off
	s_mov_b32 m0, s0
	v_lshl_add_u64 v[0:1], v[0:1], 0, s[12:13]
	s_add_i32 s87, s87, s23
	s_mov_b32 s0, m0
	s_mov_b32 m0, s87
	s_nop 0
	global_load_lds_dwordx4 v[0:1], off
	s_mov_b32 m0, s0
	v_and_b32_e32 v0, 0x118, v11
	v_and_b32_e32 v14, 0xc0, v12
	s_movk_i32 s0, 0x70
	v_and_or_b32 v0, v13, 32, v0
	v_and_b32_e32 v1, 0x70, v12
	v_bitop3_b32 v221, v210, v12, s0 bitop3:0x78
	s_movk_i32 s0, 0xc0
	v_add3_u32 v230, v14, s84, v0
	v_mov_b32_e32 v14, v211
	v_mov_b32_e32 v15, v211
	v_bitop3_b32 v222, v210, v1, 32 bitop3:0x36
	v_bitop3_b32 v223, v210, v1, 64 bitop3:0x36
	v_bitop3_b32 v225, v210, v1, s38 bitop3:0x36
	v_bitop3_b32 v226, v210, v1, s39 bitop3:0x36
	v_bitop3_b32 v227, v210, v1, s40 bitop3:0x36
	v_bitop3_b32 v228, v210, v1, s0 bitop3:0x36
	v_bitop3_b32 v229, v210, v1, s41 bitop3:0x36
	v_and_b32_e32 v236, 0x80, v12
	v_xor_b32_e32 v221, v236, v221
	v_xor_b32_e32 v222, v236, v222
	v_xor_b32_e32 v223, v236, v223
	v_xor_b32_e32 v225, v236, v225
	v_xor_b32_e32 v226, v236, v226
	v_xor_b32_e32 v227, v236, v227
	v_xor_b32_e32 v228, v236, v228
	v_xor_b32_e32 v229, v236, v229
	v_cmp_gt_u32_e64 s[0:1], 32, v10
	s_add_u32 s84, s74, s4
	v_mov_b32_e32 v0, v211
	v_mov_b32_e32 v1, v211
	v_mov_b32_e32 v2, v211
	v_mov_b32_e32 v3, v211
	v_mov_b32_e32 v4, v211
	v_mov_b32_e32 v5, v211
	v_mov_b32_e32 v6, v211
	v_mov_b32_e32 v7, v211
	v_mov_b32_e32 v8, v211
	v_mov_b32_e32 v9, v211
	v_mov_b32_e32 v10, v211
	v_mov_b32_e32 v11, v211
	v_mov_b32_e32 v12, v211
	v_mov_b32_e32 v13, v211
	v_mov_b64_e32 v[126:127], v[14:15]
	v_mov_b64_e32 v[110:111], v[14:15]
	v_mov_b64_e32 v[94:95], v[14:15]
	v_mov_b64_e32 v[78:79], v[14:15]
	v_mov_b64_e32 v[62:63], v[14:15]
	v_mov_b64_e32 v[46:47], v[14:15]
	v_mov_b64_e32 v[30:31], v[14:15]
	s_mov_b32 s78, 2
	s_mov_b32 s80, 0
	v_lshlrev_b32_e32 v220, 8, v219
	v_lshl_add_u32 v224, v219, 2, s21
	s_addc_u32 s85, s75, s5
	v_mov_b32_e32 v232, 0
	v_mov_b32_e32 v231, 0xf149f2ca
	s_mov_b64 s[22:23], 0
	v_mov_b64_e32 v[124:125], v[12:13]
	v_mov_b64_e32 v[122:123], v[10:11]
	v_mov_b64_e32 v[120:121], v[8:9]
	v_mov_b64_e32 v[118:119], v[6:7]
	v_mov_b64_e32 v[116:117], v[4:5]
	v_mov_b64_e32 v[114:115], v[2:3]
	v_mov_b64_e32 v[112:113], v[0:1]
	v_mov_b64_e32 v[108:109], v[12:13]
	v_mov_b64_e32 v[106:107], v[10:11]
	v_mov_b64_e32 v[104:105], v[8:9]
	v_mov_b64_e32 v[102:103], v[6:7]
	v_mov_b64_e32 v[100:101], v[4:5]
	v_mov_b64_e32 v[98:99], v[2:3]
	v_mov_b64_e32 v[96:97], v[0:1]
	v_mov_b64_e32 v[92:93], v[12:13]
	v_mov_b64_e32 v[90:91], v[10:11]
	v_mov_b64_e32 v[88:89], v[8:9]
	v_mov_b64_e32 v[86:87], v[6:7]
	v_mov_b64_e32 v[84:85], v[4:5]
	v_mov_b64_e32 v[82:83], v[2:3]
	v_mov_b64_e32 v[80:81], v[0:1]
	v_mov_b64_e32 v[76:77], v[12:13]
	v_mov_b64_e32 v[74:75], v[10:11]
	v_mov_b64_e32 v[72:73], v[8:9]
	v_mov_b64_e32 v[70:71], v[6:7]
	v_mov_b64_e32 v[68:69], v[4:5]
	v_mov_b64_e32 v[66:67], v[2:3]
	v_mov_b64_e32 v[64:65], v[0:1]
	v_mov_b64_e32 v[60:61], v[12:13]
	v_mov_b64_e32 v[58:59], v[10:11]
	v_mov_b64_e32 v[56:57], v[8:9]
	v_mov_b64_e32 v[54:55], v[6:7]
	v_mov_b64_e32 v[52:53], v[4:5]
	v_mov_b64_e32 v[50:51], v[2:3]
	v_mov_b64_e32 v[48:49], v[0:1]
	v_mov_b64_e32 v[44:45], v[12:13]
	v_mov_b64_e32 v[42:43], v[10:11]
	v_mov_b64_e32 v[40:41], v[8:9]
	v_mov_b64_e32 v[38:39], v[6:7]
	v_mov_b64_e32 v[36:37], v[4:5]
	v_mov_b64_e32 v[34:35], v[2:3]
	v_mov_b64_e32 v[32:33], v[0:1]
	v_mov_b64_e32 v[28:29], v[12:13]
	v_mov_b64_e32 v[26:27], v[10:11]
	v_mov_b64_e32 v[24:25], v[8:9]
	v_mov_b64_e32 v[22:23], v[6:7]
	v_mov_b64_e32 v[20:21], v[4:5]
	v_mov_b64_e32 v[18:19], v[2:3]
	v_mov_b64_e32 v[16:17], v[0:1]
	s_mov_b32 s86, 0
	s_cmp_eq_u32 s22, 0x7e0000
	s_mov_b64 s[4:5], -1
	s_cbranch_scc0 .LBB0_912

.LBB0_905:
	s_lshl_b32 s24, s78, 14
	s_add_i32 s24, s79, s24
	s_mov_b32 m0, s24
	s_add_u32 s96, s84, s22
	s_addc_u32 s97, s85, s23
	global_load_lds_dwordx4 v213, s[96:97]
	s_add_i32 m0, s24, 0x400
	s_add_u32 s4, s76, s22
	s_addc_u32 s5, s77, s23
	s_add_u32 s4, s4, 0x26840000
	s_addc_u32 s5, s5, 0
	global_load_lds_dwordx4 v215, s[96:97]
	s_lshl_b32 s24, s78, 15
	s_add_i32 s24, s81, s24
	s_mov_b32 m0, s24
	s_add_u32 s96, s4, s8
	s_addc_u32 s97, s5, s9
	global_load_lds_dwordx4 v217, s[4:5]
	s_add_i32 m0, s24, 0x400
	s_nop 0
	global_load_lds_dwordx4 v217, s[96:97]
	s_add_i32 m0, s24, 0x800
	s_add_u32 s96, s4, s10
	s_addc_u32 s97, s5, s11
	global_load_lds_dwordx4 v217, s[96:97]
	s_add_i32 m0, s24, 0xc00
	s_add_u32 s96, s4, s12
	s_addc_u32 s97, s5, s13
	global_load_lds_dwordx4 v217, s[96:97]
